# up-GEMM column tiles rotated by 4 per 8-row group (different XCDs stream different weight tiles at the same time)
# baseline (speedup 1.0000x reference)
.LBB0_330:
	s_cmpk_lt_i32 s86, 0x28a
	s_cselect_b64 s[4:5], -1, 0
	v_writelane_b32 v252, s4, 6
	s_ashr_i32 s87, s86, 31
	s_ashr_i32 s89, s85, 31
	v_writelane_b32 v252, s5, 7
	s_lshr_b32 s4, s87, 29
	s_add_i32 s5, s86, s4
	s_ashr_i32 s4, s5, 3
	s_and_b32 s5, s5, -8
	s_sub_i32 s5, s86, s5
	s_mul_i32 s6, s5, 0x51
	s_add_i32 s6, s6, 2
	s_add_u32 s96, s0, 0x4200
	s_addc_u32 s97, s1, 0
	s_add_u32 s8, s0, 0x4400
	s_addc_u32 s9, s1, 0
	v_writelane_b32 v252, s8, 8
	s_mul_hi_i32 s77, s94, 0x2800
	v_writelane_b32 v255, s88, 0
	v_writelane_b32 v252, s9, 9
	s_add_u32 s8, s0, 0x4500
	s_addc_u32 s9, s1, 0
	v_writelane_b32 v252, s8, 10
	s_mul_i32 s76, s94, 0x2800
	s_mov_b32 s29, 0
	v_writelane_b32 v252, s9, 11
	s_add_u32 s8, s0, 0x4600
	s_addc_u32 s9, s1, 0
	v_writelane_b32 v252, s8, 12
	v_mov_b32_e32 v96, 0
	v_mov_b32_e32 v176, 0x3ecc95a3
	v_writelane_b32 v252, s9, 13
	s_add_u32 s8, s0, 0x4700
	s_addc_u32 s9, s1, 0
	v_writelane_b32 v252, s8, 14
	v_mov_b32_e32 v177, 0x358637bd
	v_mov_b32_e32 v234, 0x260
	v_writelane_b32 v252, s9, 15
	s_add_u32 s8, s0, 0x4800
	s_addc_u32 s9, s1, 0
	v_writelane_b32 v252, s8, 16
	v_mov_b32_e32 v178, 0x40135761
	v_mov_b32_e32 v179, 0x7f800000
	v_writelane_b32 v252, s9, 17
	s_add_u32 s8, s0, 0x4900
	s_addc_u32 s9, s1, 0
	v_writelane_b32 v252, s8, 18
	v_mov_b32_e32 v146, 0x3f317218
	v_mov_b32_e32 v181, 0xff800000
	v_writelane_b32 v252, s9, 19
	s_add_u32 s8, s0, 0x4a00
	s_addc_u32 s9, s1, 0
	v_writelane_b32 v252, s8, 20
	v_mov_b32_e32 v183, 0x400
	v_mov_b32_e32 v182, 0x800
	v_writelane_b32 v252, s9, 21
	s_add_u32 s8, s0, 0x4b00
	s_addc_u32 s9, s1, 0
	v_writelane_b32 v252, s8, 22
	v_mov_b32_e32 v184, 0xc00
	s_mov_b32 s78, 0x10000
	v_writelane_b32 v252, s9, 23
	s_add_u32 s8, s0, 0x4c00
	s_addc_u32 s9, s1, 0
	v_writelane_b32 v252, s8, 24
	s_movk_i32 s79, 0x1000
	s_movk_i32 s40, 0x7f
	v_writelane_b32 v252, s9, 25
	s_add_u32 s8, s0, 0x4d00
	s_addc_u32 s9, s1, 0
	v_writelane_b32 v252, s8, 26
	s_movk_i32 s42, 0x2800
	s_mov_b32 s43, 0xbfb8aa3b
	v_writelane_b32 v252, s9, 27
	s_add_u32 s8, s0, 0x4e00
	s_addc_u32 s9, s1, 0
	v_writelane_b32 v252, s8, 28
	s_mov_b32 s34, 0x42ce8ed0
	s_mov_b32 s35, 0xc2b17218
	v_writelane_b32 v252, s9, 29
	s_add_u32 s8, s0, 0x4f00
	s_addc_u32 s9, s1, 0
	v_writelane_b32 v252, s8, 30
	s_movk_i32 s36, 0x7fff
	s_mov_b32 s68, 0xffff0000
	v_writelane_b32 v252, s9, 31
	s_add_u32 s8, s0, 0x5000
	s_addc_u32 s9, s1, 0
	v_writelane_b32 v252, s8, 32
	s_movk_i32 s69, 0x810
	s_mov_b32 s22, 0xff800000
	v_writelane_b32 v252, s9, 33
	s_add_u32 s8, s0, 0x5100
	s_addc_u32 s9, s1, 0
	v_writelane_b32 v252, s8, 34
	s_movk_i32 s70, 0x81
	s_mov_b32 s23, 0x1da6f000
	v_writelane_b32 v252, s9, 35
	s_add_u32 s8, s0, 0x5200
	s_addc_u32 s9, s1, 0
	v_writelane_b32 v252, s8, 36
	s_movk_i32 s30, 0xffdf
	s_mov_b32 s26, 0x41000000
	v_writelane_b32 v252, s9, 37
	s_add_u32 s8, s0, 0x5300
	s_addc_u32 s9, s1, 0
	v_writelane_b32 v252, s8, 38
	s_cmp_eq_u32 s33, 15
	s_mov_b32 s53, 0xf800000
	v_writelane_b32 v252, s9, 39
	s_cselect_b64 s[8:9], -1, 0
	v_writelane_b32 v252, s8, 40
	s_cmp_eq_u32 s33, 14
	s_mov_b64 s[58:59], 0x80
	v_writelane_b32 v252, s9, 41
	s_cselect_b64 s[8:9], -1, 0
	v_writelane_b32 v252, s8, 42
	s_cmp_eq_u32 s33, 13
	s_nop 0
	v_writelane_b32 v252, s9, 43
	s_cselect_b64 s[8:9], -1, 0
	v_writelane_b32 v252, s8, 44
	s_cmp_eq_u32 s33, 12
	s_nop 0
	v_writelane_b32 v252, s9, 45
	s_cselect_b64 s[8:9], -1, 0
	v_writelane_b32 v252, s8, 46
	s_cmp_eq_u32 s33, 11
	s_nop 0
	v_writelane_b32 v252, s9, 47
	s_cselect_b64 s[8:9], -1, 0
	v_writelane_b32 v252, s8, 48
	s_cmp_eq_u32 s33, 10
	s_nop 0
	v_writelane_b32 v252, s9, 49
	s_cselect_b64 s[8:9], -1, 0
	v_writelane_b32 v252, s8, 50
	s_cmp_eq_u32 s33, 9
	s_nop 0
	v_writelane_b32 v252, s9, 51
	s_cselect_b64 s[8:9], -1, 0
	v_writelane_b32 v252, s8, 52
	s_cmp_eq_u32 s33, 8
	s_nop 0
	v_writelane_b32 v252, s9, 53
	s_cselect_b64 s[8:9], -1, 0
	v_writelane_b32 v252, s8, 54
	s_cmp_eq_u32 s33, 7
	s_nop 0
	v_writelane_b32 v252, s9, 55
	s_cselect_b64 s[8:9], -1, 0
	v_writelane_b32 v252, s8, 56
	s_cmp_eq_u32 s33, 6
	s_nop 0
	v_writelane_b32 v252, s9, 57
	s_cselect_b64 s[8:9], -1, 0
	v_writelane_b32 v252, s8, 58
	s_cmp_eq_u32 s33, 5
	s_nop 0
	v_writelane_b32 v252, s9, 59
	s_cselect_b64 s[8:9], -1, 0
	v_writelane_b32 v252, s8, 60
	s_cmp_eq_u32 s33, 4
	s_nop 0
	v_writelane_b32 v252, s9, 61
	s_cselect_b64 s[8:9], -1, 0
	v_writelane_b32 v252, s8, 62
	s_cmp_eq_u32 s33, 3
	s_nop 0
	v_writelane_b32 v252, s9, 63
	s_cselect_b64 s[8:9], -1, 0
	v_writelane_b32 v253, s8, 0
	s_cmp_eq_u32 s33, 2
	s_nop 0
	v_writelane_b32 v253, s9, 1
	s_cselect_b64 s[8:9], -1, 0
	v_writelane_b32 v253, s8, 2
	s_cmp_eq_u32 s33, 1
	s_nop 0
	v_writelane_b32 v253, s9, 3
	s_cselect_b64 s[8:9], -1, 0
	v_writelane_b32 v253, s8, 4
	s_cmp_eq_u32 s33, 0
	s_nop 0
	v_writelane_b32 v253, s9, 5
	s_cselect_b64 s[8:9], -1, 0
	s_lshl_b32 s7, s33, 8
	s_add_u32 s2, s2, s7
	v_writelane_b32 v253, s8, 6
	s_addc_u32 s3, s3, 0
	s_nop 0
	v_writelane_b32 v253, s9, 7
	s_add_u32 s8, s2, 0x1400
	s_addc_u32 s9, s3, 0
	v_writelane_b32 v253, s8, 8
	s_add_u32 s2, s2, 0x2400
	s_addc_u32 s3, s3, 0
	v_writelane_b32 v253, s9, 9
	v_writelane_b32 v253, s2, 10
	v_readlane_b32 s9, v252, 5
	s_nop 0
	v_writelane_b32 v253, s3, 11
	s_add_u32 s2, s0, 0x7400
	s_addc_u32 s3, s1, 0
	v_writelane_b32 v253, s2, 12
	s_add_u32 s0, s0, 0x7500
	s_addc_u32 s1, s1, 0
	v_writelane_b32 v253, s3, 13
	v_writelane_b32 v253, s0, 14
	s_cmpk_gt_i32 s86, 0xff
	s_nop 0
	v_writelane_b32 v253, s1, 15
	s_cselect_b64 s[0:1], -1, 0
	v_writelane_b32 v253, s0, 16
	s_cmpk_lt_u32 s48, 0x100
	s_nop 0
	v_writelane_b32 v253, s1, 17
	s_cselect_b64 s[0:1], -1, 0
	v_writelane_b32 v253, s0, 18
	s_nop 1
	v_writelane_b32 v253, s1, 19
	s_bfe_u32 s0, s48, 0x20006
	s_lshl_b32 s1, s88, 7
	s_lshl_b32 s80, s0, 5
	s_cmp_eq_u32 s0, 0
	s_cselect_b64 s[82:83], -1, 0
	s_cmp_lg_u32 s0, 0
	v_writelane_b32 v253, s1, 20
	s_cselect_b64 s[2:3], -1, 0
	v_writelane_b32 v253, s2, 21
	s_cmp_gt_u32 s0, 1
	s_nop 0
	v_writelane_b32 v253, s3, 22
	s_cselect_b64 s[2:3], -1, 0
	v_writelane_b32 v253, s2, 23
	s_cmp_eq_u32 s0, 3
	s_nop 0
	v_writelane_b32 v253, s3, 24
	s_cselect_b64 s[2:3], -1, 0
	s_lshr_b32 s81, s48, 8
	s_lshl_b32 s1, s81, 14
	s_add_i32 s84, 0, 0x10000
	v_writelane_b32 v253, s2, 25
	s_add_i32 s1, s84, s1
	s_cmp_eq_u32 s0, 1
	v_writelane_b32 v253, s3, 26
	v_writelane_b32 v253, s1, 27
	s_cselect_b64 s[2:3], -1, 0
	v_writelane_b32 v253, s2, 28
	s_cmp_eq_u32 s0, 2
	s_cselect_b64 s[0:1], -1, 0
	v_writelane_b32 v253, s3, 29
	v_writelane_b32 v253, s0, 30
	s_lshl_b32 s15, s88, 12
	s_nop 0
	v_writelane_b32 v253, s1, 31
	s_add_i32 s0, s84, s15
	s_cmpk_lt_i32 s9, 0x1000
	v_writelane_b32 v253, s0, 32
	s_cselect_b64 s[0:1], -1, 0
	v_writelane_b32 v253, s0, 33
	s_cmpk_lt_i32 s9, 0x800
	s_nop 0
	v_writelane_b32 v253, s1, 34
	s_cselect_b64 s[0:1], -1, 0
	v_writelane_b32 v253, s0, 35
	s_cmpk_lt_i32 s86, 0x80
	s_nop 0
	v_writelane_b32 v253, s1, 36
	s_cselect_b64 s[0:1], -1, 0
	v_writelane_b32 v253, s0, 37
	s_nop 1
	v_writelane_b32 v253, s1, 38
	s_lshl_b32 s0, s88, 4
	s_cmpk_lg_i32 s85, 0x100
	v_writelane_b32 v253, s0, 39
	s_cselect_b64 s[2:3], -1, 0
	s_lshl_b32 s0, s86, 9
	s_cmpk_gt_u32 s86, 0x7f
	v_writelane_b32 v253, s0, 40
	s_cselect_b64 s[0:1], -1, 0
	s_or_b64 s[0:1], s[0:1], s[2:3]
	v_writelane_b32 v253, s0, 41
	s_lshl_b32 s72, s88, 10
	s_lshl_b32 s16, s88, 5
	v_writelane_b32 v253, s1, 42
	s_lshl_b32 s0, s88, 13
	s_add_i32 s41, s0, 0
	s_lshl_b32 s0, s90, 2
	s_add_i32 s0, s84, s0
	v_writelane_b32 v253, s0, 43
	s_add_i32 s0, s88, 8
	s_lshl_b32 s1, s0, 5
	v_writelane_b32 v253, s1, 44
	s_lshl_b32 s0, s0, 3
	v_writelane_b32 v253, s0, 45
	s_lshl_b32 s0, s85, 9
	v_writelane_b32 v253, s0, 46
	s_lshl_b32 s0, s88, 3
	s_cmp_lt_u32 s48, 64
	v_writelane_b32 v253, s0, 47
	s_cselect_b64 s[0:1], -1, 0
	v_writelane_b32 v253, s0, 48
	s_lshl_b32 s17, s88, 8
	s_nop 0
	v_writelane_b32 v253, s1, 49
	s_add_i32 s0, s84, s17
	s_cmpk_lt_i32 s9, 0x100
	v_writelane_b32 v253, s0, 50
	s_cselect_b64 s[0:1], -1, 0
	v_writelane_b32 v253, s0, 51
	s_add_i32 s7, s86, 0xffffff00
	s_add_i32 s18, s9, 0x4000
	v_writelane_b32 v253, s1, 52
	s_mul_i32 s0, s86, 7
	s_add_i32 s8, s7, s0
	s_cmpk_eq_i32 s85, 0x100
	s_cselect_b64 s[0:1], -1, 0
	v_writelane_b32 v253, s0, 53
	s_nop 1
	v_writelane_b32 v253, s1, 54
	s_and_b64 s[0:1], s[0:1], exec
	s_cselect_b32 s1, 64, s85
	s_cselect_b32 s10, s8, s49
	s_cselect_b32 s0, 0x700, s94
	s_cmp_ge_i32 s86, s1
	v_writelane_b32 v253, s0, 55
	s_cselect_b64 s[8:9], -1, 0
	v_writelane_b32 v253, s8, 56
	s_mul_i32 s0, s88, 0xffffe004
	s_add_i32 s14, s41, s0
	v_writelane_b32 v253, s9, 57
	s_lshl_b32 s0, s1, 9
	s_ashr_i32 s91, s90, 31
	v_writelane_b32 v253, s0, 58
	s_and_b32 s0, s16, 0x7fffff80
	s_cmpk_lt_i32 s86, 0x100
	s_cselect_b64 s[8:9], -1, 0
	v_writelane_b32 v253, s8, 59
	s_nop 1
	v_writelane_b32 v253, s9, 60
	s_and_b64 s[8:9], s[8:9], exec
	s_cselect_b32 s8, s86, 0
	s_ashr_i32 s9, s8, 31
	s_lshr_b32 s9, s9, 29
	s_add_i32 s9, s8, s9
	s_and_b32 s11, s9, -8
	s_sub_i32 s11, s8, s11
	s_ashr_i32 s8, s7, 31
	s_lshr_b32 s8, s8, 30
	s_waitcnt lgkmcnt(0)
	s_add_i32 s13, s7, s8
	s_and_b32 s8, s13, -4
	v_writelane_b32 v253, s8, 61
	s_sub_i32 s7, s7, s8
	s_ashr_i32 s12, s9, 3
	v_writelane_b32 v253, s7, 62
	s_lshl_b32 s7, s11, 5
	s_cmpk_lt_i32 s86, 0x110
	s_cselect_b64 s[8:9], -1, 0
	v_writelane_b32 v253, s8, 63
	s_cmpk_lt_i32 s86, 0x820
	s_nop 0
	v_writelane_b32 v254, s9, 0
	s_cselect_b64 s[8:9], -1, 0
	v_writelane_b32 v254, s8, 1
	s_cmp_gt_u32 s86, 31
	s_nop 0
	v_writelane_b32 v254, s9, 2
	s_cselect_b64 s[8:9], -1, 0
	s_or_b64 s[2:3], s[8:9], s[2:3]
	s_mul_i32 s8, s88, 0x3ffc
	s_add_i32 s9, s10, s88
	v_writelane_b32 v254, s14, 3
	s_add_i32 s8, s14, s8
	v_writelane_b32 v254, s8, 4
	s_cmpk_lt_i32 s9, 0x1f00
	v_writelane_b32 v254, s9, 5
	s_cselect_b64 s[8:9], -1, 0
	s_lshl_b32 s10, s13, 1
	s_and_b32 s10, s10, -8
	s_cmpk_lt_i32 s86, 0x120
	v_writelane_b32 v254, s10, 6
	s_cselect_b64 s[20:21], -1, 0
	v_writelane_b32 v254, s20, 7
	s_add_i32 s13, s72, 0
	s_bfe_u32 s10, s48, 0x30006
	v_writelane_b32 v254, s21, 8
	v_writelane_b32 v254, s13, 9
	s_add_i32 s13, s13, 0x13b80
	v_writelane_b32 v254, s13, 10
	s_cmp_lt_i32 s5, 2
	s_mul_i32 s13, s5, 0x52
	s_cselect_b32 s6, s13, s6
	s_add_i32 s6, s6, s4
	s_mul_hi_i32 s13, s6, 0x66666667
	s_lshr_b32 s14, s13, 31
	s_ashr_i32 s13, s13, 5
	s_add_i32 s13, s13, s14
	s_mul_i32 s14, s13, 0x50
	s_lshl_b32 s13, s13, 3
	s_sub_i32 s6, s6, s14
	s_sub_i32 s14, 0x41, s13
	s_min_u32 s14, s14, 8
	s_cmp_eq_u32 s10, 0
	s_cselect_b64 s[74:75], -1, 0
	s_cmp_lt_i32 s11, 0
	s_mul_i32 s11, s11, 33
	s_cselect_b32 s7, s11, s7
	s_add_i32 s7, s7, s12
	s_ashr_i32 s10, s7, 31
	s_lshr_b32 s10, s10, 27
	s_add_i32 s10, s7, s10
	s_and_b32 s11, s10, 0xffe0
	s_sub_i32 s7, s7, s11
	s_bfe_i32 s11, s7, 0x80000
	s_bfe_u32 s11, s11, 0x3000c
	s_add_i32 s11, s7, s11
	s_and_b32 s12, s11, 0xf8
	s_sub_i32 s7, s7, s12
	s_ashr_i32 s10, s10, 5
	s_lshl_b32 s10, s10, 3
	s_sext_i32_i8 s7, s7
	s_add_i32 s7, s10, s7
	v_writelane_b32 v254, s7, 11
	s_bfe_i32 s7, s11, 0x80000
	s_sext_i32_i16 s7, s7
	s_ashr_i32 s7, s7, 3
	v_writelane_b32 v254, s7, 12
	s_cmp_lt_i32 s5, 0
	s_movk_i32 s7, 0x105
	s_cselect_b32 s7, s7, 0x104
	s_and_b64 s[2:3], s[2:3], s[8:9]
	v_writelane_b32 v254, s2, 13
	v_cvt_f32_ubyte0_e32 v1, s14
	v_cvt_f32_i32_e32 v0, s6
	v_writelane_b32 v254, s3, 14
	s_mul_i32 s2, s5, s7
	s_add_i32 s2, s2, s4
	s_ashr_i32 s3, s2, 31
	s_lshr_b32 s3, s3, 24
	v_rcp_iflag_f32_e32 v2, v1
	s_add_i32 s3, s2, s3
	s_and_b32 s4, s3, 0xffffff00
	s_sub_i32 s7, s2, s4
	s_ashr_i32 s2, s3, 8
	s_lshl_b32 s8, s2, 3
	v_mul_f32_e32 v2, v0, v2
	s_sub_i32 s2, 0x41, s8
	v_trunc_f32_e32 v2, v2
	s_min_u32 s9, s2, 8
	s_ashr_i32 s2, s6, 30
	v_fma_f32 v0, -v2, v1, v0
	s_or_b32 s4, s2, 1
	v_cmp_ge_f32_e64 s[2:3], |v0|, v1
	v_cvt_i32_f32_e32 v0, v2
	s_and_b64 s[2:3], s[2:3], exec
	s_cselect_b32 s2, s4, 0
	v_cvt_f32_ubyte0_e32 v1, s9
	v_readfirstlane_b32 s3, v0
	s_add_i32 s2, s3, s2
	s_mul_i32 s3, s2, s14
	s_sub_i32 s3, s6, s3
	s_sext_i32_i8 s3, s3
	v_cvt_f32_i32_e32 v0, s7
	v_rcp_iflag_f32_e32 v2, v1
	s_bfe_i64 s[4:5], s[2:3], 0x80000
	s_lshl_b64 s[4:5], s[4:5], 19
	s_add_i32 s10, s13, s3
	v_writelane_b32 v254, s4, 15
	s_ashr_i32 s11, s10, 31
	v_mul_f32_e32 v2, v0, v2
	v_writelane_b32 v254, s5, 16
	s_mov_b32 s4, s10
	v_writelane_b32 v254, s4, 17
	v_trunc_f32_e32 v2, v2
	v_fma_f32 v0, -v2, v1, v0
	v_writelane_b32 v254, s5, 18
	s_lshl_b64 s[4:5], s[10:11], 19
	v_writelane_b32 v254, s4, 19
	s_ashr_i32 s3, s7, 30
	s_or_b32 s3, s3, 1
	v_writelane_b32 v254, s5, 20
	v_cmp_ge_f32_e64 s[4:5], |v0|, v1
	v_cvt_i32_f32_e32 v0, v2
	s_and_b64 s[4:5], s[4:5], exec
	s_sext_i32_i8 s2, s2
	v_writelane_b32 v254, s2, 21
	s_cselect_b32 s2, s3, 0
	v_readfirstlane_b32 s3, v0
	s_add_i32 s2, s3, s2
	s_mul_i32 s3, s2, s9
	s_sub_i32 s3, s7, s3
	s_sext_i32_i16 s3, s3
	s_add_i32 s3, s8, s3
	s_bitcmp1_b32 s86, 0
	v_writelane_b32 v254, s3, 22
	s_cselect_b64 s[4:5], -1, 0
	v_writelane_b32 v254, s4, 23
	s_bitcmp1_b32 s85, 0
	s_sext_i32_i16 s2, s2
	v_writelane_b32 v254, s5, 24
	s_cselect_b64 s[4:5], -1, 0
	v_writelane_b32 v254, s4, 25
	s_lshl_b32 s3, s86, 5
	s_lshl_b32 s0, s0, 1
	v_writelane_b32 v254, s5, 26
	s_lshl_b32 s4, s88, 2
	s_add_i32 s3, s3, s4
	v_writelane_b32 v254, s3, 27
	v_readlane_b32 s3, v254, 22
	s_lshr_b32 s3, s3, 3
	s_lshl_b32 s3, s3, 2
	s_add_i32 s2, s2, s3
	s_and_b32 s2, s2, 31
	v_writelane_b32 v254, s2, 28
	s_add_i32 s2, s15, 0
	v_writelane_b32 v254, s15, 29
	s_add_i32 s3, s2, 0x10030
	v_writelane_b32 v254, s3, 30
	s_add_i32 s3, s2, 0x10130
	v_writelane_b32 v254, s3, 31
	s_add_i32 s3, s2, 0x10230
	v_writelane_b32 v254, s3, 32
	s_add_i32 s2, s2, 0x10330
	v_writelane_b32 v254, s2, 33
	s_mul_hi_i32 s3, s18, 0x2800
	s_mul_i32 s2, s18, 0x2800
	v_writelane_b32 v254, s2, 34
	s_ashr_i32 s19, s18, 31
	s_ashr_i32 s95, s94, 31
	v_writelane_b32 v254, s3, 35
	s_lshl_b32 s2, s1, 10
	v_writelane_b32 v254, s2, 36
	s_mulk_i32 s1, 0x600
	v_writelane_b32 v254, s1, 37
	s_lshl_b32 s1, s86, 11
	v_writelane_b32 v254, s17, 38
	s_add_i32 s1, s1, s17
	v_writelane_b32 v254, s1, 39
	s_lshl_b32 s1, s86, 8
	v_writelane_b32 v254, s16, 40
	s_add_i32 s1, s1, s16
	v_writelane_b32 v254, s1, 41
	v_writelane_b32 v254, s0, 42
	s_add_i32 s0, s90, 0xfffffe00
	v_writelane_b32 v254, s0, 43
	s_lshl_b32 s0, s85, 11
	v_writelane_b32 v254, s0, 44
	s_lshl_b32 s0, s85, 5
	v_writelane_b32 v254, s0, 45
	s_lshl_b32 s0, s85, 8
	v_writelane_b32 v254, s0, 46
	s_add_i32 s0, 0, 0x18800
	v_writelane_b32 v254, s0, 47
	s_add_i32 s0, 0, 0x19000
	v_writelane_b32 v254, s0, 48
	s_add_i32 s0, 0, 0x15b80
	v_writelane_b32 v254, s0, 49
	s_add_i32 s0, 0, 0x13010
	v_writelane_b32 v254, s0, 50
	s_add_i32 s0, 0, 0x13b40
	v_writelane_b32 v254, s0, 51
	s_add_i32 s0, 0, 0x13b44
	v_writelane_b32 v254, s0, 52
	s_add_i32 s0, 0, 0x20300
	v_writelane_b32 v254, s0, 53
	s_add_i32 s0, 0, 0xc840
	v_writelane_b32 v254, s0, 54
	s_mov_b32 s0, s18
	v_writelane_b32 v254, s0, 55
	v_writelane_b32 v255, s90, 1
	s_mov_b32 s2, s86
	v_writelane_b32 v254, s1, 56
	s_lshl_b64 s[0:1], s[18:19], 11
	v_writelane_b32 v254, s0, 57
	v_writelane_b32 v255, s91, 2
	v_writelane_b32 v255, s92, 3
	v_writelane_b32 v254, s1, 58
	s_mov_b64 s[0:1], 0
	v_writelane_b32 v254, s0, 59
	v_writelane_b32 v255, s93, 4
	s_lshl_b64 s[50:51], s[94:95], 11
	v_writelane_b32 v254, s1, 60
	v_writelane_b32 v254, s2, 61
	v_mbcnt_lo_u32_b32 v0, -1, 0
	v_mbcnt_hi_u32_b32 v180, -1, v0
	v_writelane_b32 v254, s3, 62
	s_mov_b32 s2, s94
	v_writelane_b32 v255, s2, 5
	s_mov_b64 s[0:1], 0x200000
	s_mov_b32 s4, s29
	v_writelane_b32 v255, s3, 6
	v_writelane_b32 v255, s87, 7
	v_writelane_b32 v255, s89, 8
	v_writelane_b32 v255, s96, 9
	v_writelane_b32 v254, s85, 63
	s_nop 0
	v_writelane_b32 v255, s97, 10
	v_writelane_b32 v255, s80, 11
	v_writelane_b32 v255, s82, 12
	s_nop 1
	v_writelane_b32 v255, s83, 13
	v_writelane_b32 v255, s81, 14
	v_writelane_b32 v255, s84, 15
	v_writelane_b32 v255, s72, 16
	v_writelane_b32 v255, s74, 17
	s_nop 1
	v_writelane_b32 v255, s75, 18
	v_writelane_b32 v255, s76, 19
	s_nop 1
	v_writelane_b32 v255, s77, 20
	v_writelane_b32 v255, s50, 21
	s_nop 1
	v_writelane_b32 v255, s51, 22
	s_branch .LBB0_334

.LBB0_1513:
	s_add_i32 s82, s82, 1
	s_mul_i32 s2, s82, s89
	s_mul_hi_u32 s3, s82, s85
	s_add_i32 s3, s3, s2
	s_mul_i32 s2, s82, s85
	s_add_u32 s4, s2, s86
	s_addc_u32 s5, s3, s87
	v_mov_b64_e32 v[0:1], 0x820
	v_cmp_lt_i64_e64 s[48:49], s[4:5], v[0:1]
	v_mov_b64_e32 v[0:1], 0x81f
	v_cmp_gt_i64_e32 vcc, s[4:5], v[0:1]
	s_cbranch_vccnz .LBB0_1515
	s_ashr_i32 s2, s4, 31
	s_lshr_b32 s2, s2, 29
	s_add_i32 s2, s4, s2
	s_ashr_i32 s3, s2, 3
	s_and_b32 s2, s2, -8
	s_sub_i32 s2, s4, s2
	s_cmp_lt_i32 s2, 0
	s_movk_i32 s4, 0x105
	s_cselect_b32 s4, s4, 0x104
	s_mul_i32 s2, s2, s4
	s_add_i32 s2, s2, s3
	s_ashr_i32 s3, s2, 31
	s_lshr_b32 s3, s3, 24
	s_add_i32 s3, s2, s3
	s_ashr_i32 s4, s3, 8
	s_lshl_b32 s4, s4, 3
	s_sub_i32 s5, 0x41, s4
	s_min_i32 s5, s5, 8
	s_abs_i32 s33, s5
	v_cvt_f32_u32_e32 v0, s33
	s_sub_i32 s38, 0, s33
	s_and_b32 s3, s3, 0xffffff00
	s_sub_i32 s2, s2, s3
	v_rcp_iflag_f32_e32 v0, v0
	s_abs_i32 s3, s2
	s_xor_b32 s37, s2, s5
	s_ashr_i32 s37, s37, 31
	v_mul_f32_e32 v0, 0x4f7ffffe, v0
	v_cvt_u32_f32_e32 v0, v0
	s_nop 0
	v_readfirstlane_b32 s39, v0
	s_mul_i32 s38, s38, s39
	s_mul_hi_u32 s38, s39, s38
	s_add_i32 s39, s39, s38
	s_mul_hi_u32 s38, s3, s39
	s_mul_i32 s39, s38, s33
	s_sub_i32 s3, s3, s39
	s_add_i32 s40, s38, 1
	s_sub_i32 s39, s3, s33
	s_cmp_ge_u32 s3, s33
	s_cselect_b32 s38, s40, s38
	s_cselect_b32 s3, s39, s3
	s_add_i32 s39, s38, 1
	s_cmp_ge_u32 s3, s33
	s_cselect_b32 s3, s39, s38
	s_xor_b32 s3, s3, s37
	s_sub_i32 s50, s3, s37
	s_mul_i32 s3, s50, s5
	s_sub_i32 s2, s2, s3
	s_add_i32 s44, s4, s2
	s_lshr_b32 s2, s44, 3
	s_lshl_b32 s2, s2, 2
	s_add_i32 s2, s50, s2
	s_and_b32 s50, s2, 31
